# NSA top-n bisection: the 8 queries' ballot / popcount / select chains interleaved over separate SGPR pairs, scalar count compare
# speedup vs baseline: 1.0054x; 1.0054x over previous
.LBB0_1529:
	s_add_i32 s0, s0, -1
	s_lshl_b32 s1, 1, s0
	s_or_b32 s16, s1, s52
	s_or_b32 s17, s1, s45
	s_or_b32 s18, s1, s44
	s_or_b32 s19, s1, s38
	v_cmp_le_u32_e64 s[94:95], s16, v69
	v_cmp_le_u32_e64 s[96:97], s17, v68
	v_cmp_le_u32_e64 s[98:99], s18, v14
	v_cmp_le_u32_e64 s[100:101], s19, v12
	s_bcnt1_i32_b64 s94, s[94:95]
	s_bcnt1_i32_b64 s96, s[96:97]
	s_bcnt1_i32_b64 s98, s[98:99]
	s_bcnt1_i32_b64 s100, s[100:101]
	s_cmp_gt_u32 s94, 12
	s_cselect_b32 s52, s16, s52
	s_cmp_gt_u32 s96, 12
	s_cselect_b32 s45, s17, s45
	s_cmp_gt_u32 s98, 12
	s_cselect_b32 s44, s18, s44
	s_cmp_gt_u32 s100, 12
	s_cselect_b32 s38, s19, s38
	s_or_b32 s16, s1, s31
	s_or_b32 s17, s1, s30
	s_or_b32 s18, s1, s29
	s_or_b32 s19, s1, s28
	v_cmp_le_u32_e64 s[94:95], s16, v10
	v_cmp_le_u32_e64 s[96:97], s17, v8
	v_cmp_le_u32_e64 s[98:99], s18, v6
	v_cmp_le_u32_e64 s[100:101], s19, v4
	s_bcnt1_i32_b64 s94, s[94:95]
	s_bcnt1_i32_b64 s96, s[96:97]
	s_bcnt1_i32_b64 s98, s[98:99]
	s_bcnt1_i32_b64 s100, s[100:101]
	s_cmp_gt_u32 s94, 12
	s_cselect_b32 s31, s16, s31
	s_cmp_gt_u32 s96, 12
	s_cselect_b32 s30, s17, s30
	s_cmp_gt_u32 s98, 12
	s_cselect_b32 s29, s18, s29
	s_cmp_gt_u32 s100, 12
	s_cselect_b32 s28, s19, s28
	s_cmp_gt_u32 s0, 8
	s_cbranch_scc1 .LBB0_1529
	s_mov_b64 s[0:1], 0

.LBB0_1533:
	s_add_i32 s0, s0, -1
	s_lshl_b32 s1, 1, s0
	s_or_b32 s16, s1, s52
	s_or_b32 s17, s1, s45
	v_cmp_le_u32_e64 s[94:95], s16, v69
	v_cmp_le_u32_e64 s[96:97], s16, v50
	v_cmp_le_u32_e64 s[98:99], s17, v68
	v_cmp_le_u32_e64 s[100:101], s17, v16
	s_bcnt1_i32_b64 s94, s[94:95]
	s_bcnt1_i32_b64 s96, s[96:97]
	s_add_i32 s94, s94, s96
	s_cmp_gt_u32 s94, 12
	s_cselect_b32 s52, s16, s52
	s_bcnt1_i32_b64 s98, s[98:99]
	s_bcnt1_i32_b64 s100, s[100:101]
	s_add_i32 s98, s98, s100
	s_cmp_gt_u32 s98, 12
	s_cselect_b32 s45, s17, s45
	s_or_b32 s16, s1, s44
	s_or_b32 s17, s1, s38
	v_cmp_le_u32_e64 s[94:95], s16, v14
	v_cmp_le_u32_e64 s[96:97], s16, v15
	v_cmp_le_u32_e64 s[98:99], s17, v12
	v_cmp_le_u32_e64 s[100:101], s17, v13
	s_bcnt1_i32_b64 s94, s[94:95]
	s_bcnt1_i32_b64 s96, s[96:97]
	s_add_i32 s94, s94, s96
	s_cmp_gt_u32 s94, 12
	s_cselect_b32 s44, s16, s44
	s_bcnt1_i32_b64 s98, s[98:99]
	s_bcnt1_i32_b64 s100, s[100:101]
	s_add_i32 s98, s98, s100
	s_cmp_gt_u32 s98, 12
	s_cselect_b32 s38, s17, s38
	s_or_b32 s16, s1, s31
	s_or_b32 s17, s1, s30
	v_cmp_le_u32_e64 s[94:95], s16, v10
	v_cmp_le_u32_e64 s[96:97], s16, v11
	v_cmp_le_u32_e64 s[98:99], s17, v8
	v_cmp_le_u32_e64 s[100:101], s17, v9
	s_bcnt1_i32_b64 s94, s[94:95]
	s_bcnt1_i32_b64 s96, s[96:97]
	s_add_i32 s94, s94, s96
	s_cmp_gt_u32 s94, 12
	s_cselect_b32 s31, s16, s31
	s_bcnt1_i32_b64 s98, s[98:99]
	s_bcnt1_i32_b64 s100, s[100:101]
	s_add_i32 s98, s98, s100
	s_cmp_gt_u32 s98, 12
	s_cselect_b32 s30, s17, s30
	s_or_b32 s16, s1, s29
	s_or_b32 s17, s1, s28
	v_cmp_le_u32_e64 s[94:95], s16, v6
	v_cmp_le_u32_e64 s[96:97], s16, v7
	v_cmp_le_u32_e64 s[98:99], s17, v4
	v_cmp_le_u32_e64 s[100:101], s17, v5
	s_bcnt1_i32_b64 s94, s[94:95]
	s_bcnt1_i32_b64 s96, s[96:97]
	s_add_i32 s94, s94, s96
	s_cmp_gt_u32 s94, 12
	s_cselect_b32 s29, s16, s29
	s_bcnt1_i32_b64 s98, s[98:99]
	s_bcnt1_i32_b64 s100, s[100:101]
	s_add_i32 s98, s98, s100
	s_cmp_gt_u32 s98, 12
	s_cselect_b32 s28, s17, s28
	s_cmp_lt_u32 s0, 9
	s_cbranch_scc0 .LBB0_1533
